# SSDOUT layer-1 ssd_out_item: 16 Hs state loads + D + first x/z pair hoisted above chunk_scan and decay blocks (load latency overlapped instead of exposed before the state MFMAs)
# speedup vs baseline: 1.0083x; 1.0027x over previous
.LBB0_2191:
	s_or_b64 exec, exec, s[6:7]
	global_load_dword v2, v[2:3], off
	s_nop 0
	global_load_dword v3, v[0:1], off
	v_and_b32_e32 v113, 64, v165
	v_add_u32_e32 v1, -1, v165
	v_cmp_lt_i32_e64 s[6:7], v1, v113
	v_and_b32_e32 v0, 63, v8
	v_add_u32_e32 v9, -2, v165
	v_cndmask_b32_e64 v1, v1, v165, s[6:7]
	v_lshlrev_b32_e32 v1, 2, v1
	v_cmp_lt_i32_e64 s[6:7], v9, v113
	v_lshlrev_b32_e32 v7, 2, v7
	v_add3_u32 v6, s23, v6, v7
	v_cndmask_b32_e64 v9, v9, v165, s[6:7]
	v_cmp_eq_u32_e64 s[6:7], 0, v0
	v_lshlrev_b32_e32 v9, 2, v9
	s_waitcnt vmcnt(1)
	v_mul_f32_e32 v2, 0x3fb8aa3b, v2
	v_exp_f32_e32 v2, v2
	s_waitcnt vmcnt(0)
	s_mul_i32 s98, s50, 34
	s_add_i32 s98, s98, s49
	s_ashr_i32 s99, s98, 31
	s_lshl_b64 s[98:99], s[98:99], 16
	s_lshl_b32 s100, s48, 13
	s_add_u32 s100, s34, s100
	s_addc_u32 s101, s35, 0
	s_add_u32 s98, s98, s100
	s_addc_u32 s99, s99, s101
	v_lshlrev_b32_e32 v252, 4, v111
	v_lshl_add_u32 v252, v56, 7, v252
	v_mov_b32_e32 v253, 0
	s_mov_b32 s100, 0x1000
	s_mov_b32 s101, 0
	v_lshl_add_u64 v[252:253], s[98:99], 0, v[252:253]
	v_lshl_add_u64 v[162:163], v[252:253], 0, s[24:25]
	global_load_dwordx4 v[240:243], v[252:253], off
	global_load_dwordx4 v[114:117], v[252:253], off offset:32
	global_load_dwordx4 v[130:133], v[252:253], off offset:64
	global_load_dwordx4 v[138:141], v[252:253], off offset:96
	v_lshl_add_u64 v[252:253], v[252:253], 0, s[100:101]
	global_load_dwordx4 v[244:247], v[162:163], off
	global_load_dwordx4 v[122:125], v[162:163], off offset:32
	global_load_dwordx4 v[134:137], v[162:163], off offset:64
	global_load_dwordx4 v[248:251], v[162:163], off offset:96
	v_lshl_add_u64 v[162:163], v[162:163], 0, s[100:101]
	global_load_dwordx4 v[84:87], v[252:253], off
	global_load_dwordx4 v[118:121], v[252:253], off offset:32
	global_load_dwordx4 v[126:129], v[252:253], off offset:64
	global_load_dwordx4 v[142:145], v[252:253], off offset:96
	global_load_dwordx4 v[146:149], v[162:163], off
	global_load_dwordx4 v[150:153], v[162:163], off offset:32
	global_load_dwordx4 v[154:157], v[162:163], off offset:64
	global_load_dwordx4 v[158:161], v[162:163], off offset:96
	s_lshl_b32 s98, s48, 2
	v_mov_b32_e32 v109, s98
	global_load_dword v110, v109, s[12:13] offset:32
	v_lshlrev_b32_e32 v82, 3, v111
	v_mov_b32_e32 v83, 0
	v_mov_b64_e32 v[252:253], s[8:9]
	s_lshl_b32 s100, s48, 7
	v_mad_i64_i32 v[162:163], s[98:99], v108, s44, v[252:253]
	v_lshl_add_u64 v[252:253], v[52:53], 0, v[82:83]
	v_lshl_add_u64 v[162:163], v[162:163], 0, s[100:101]
	v_lshl_add_u64 v[252:253], v[252:253], 0, s[100:101]
	v_lshl_add_u64 v[162:163], v[162:163], 0, v[82:83]
	s_mov_b32 s100, s45
	s_nop 0
	v_lshl_add_u64 v[162:163], v[162:163], 0, s[100:101]
	global_load_dwordx2 v[168:169], v[162:163], off offset:2368
	global_load_dwordx2 v[234:235], v[252:253], off
	ds_write_b32 v6, v3
	v_mul_f32_e64 v8, v3, -v2
	ds_bpermute_b32 v1, v1, v8
	s_waitcnt lgkmcnt(0)
	v_fma_f32 v1, v3, -v2, v1
	v_cndmask_b32_e64 v1, v1, v8, s[6:7]
	ds_bpermute_b32 v2, v9, v1
	v_add_u32_e32 v8, -4, v165
	v_cmp_lt_i32_e64 s[6:7], v8, v113
	s_waitcnt lgkmcnt(0)
	v_add_f32_e32 v2, v1, v2
	v_cndmask_b32_e64 v8, v8, v165, s[6:7]
	v_cmp_gt_u32_e64 s[6:7], 2, v0
	v_lshlrev_b32_e32 v8, 2, v8
	s_nop 0
	v_cndmask_b32_e64 v1, v2, v1, s[6:7]
	ds_bpermute_b32 v2, v8, v1
	v_add_u32_e32 v8, -8, v165
	v_cmp_lt_i32_e64 s[6:7], v8, v113
	s_waitcnt lgkmcnt(0)
	v_add_f32_e32 v2, v1, v2
	v_cndmask_b32_e64 v8, v8, v165, s[6:7]
	v_cmp_gt_u32_e64 s[6:7], 4, v0
	v_lshlrev_b32_e32 v8, 2, v8
	s_nop 0
	v_cndmask_b32_e64 v1, v2, v1, s[6:7]
	ds_bpermute_b32 v2, v8, v1
	v_add_u32_e32 v8, -16, v165
	v_cmp_lt_i32_e64 s[6:7], v8, v113
	s_waitcnt lgkmcnt(0)
	v_add_f32_e32 v2, v1, v2
	v_cndmask_b32_e64 v8, v8, v165, s[6:7]
	v_cmp_gt_u32_e64 s[6:7], 8, v0
	v_lshlrev_b32_e32 v8, 2, v8
	s_nop 0
	v_cndmask_b32_e64 v1, v2, v1, s[6:7]
	ds_bpermute_b32 v2, v8, v1
	v_subrev_u32_e32 v8, 32, v165
	v_cmp_lt_i32_e64 s[6:7], v8, v113
	s_waitcnt lgkmcnt(0)
	v_add_f32_e32 v2, v1, v2
	v_cndmask_b32_e64 v8, v8, v165, s[6:7]
	v_cmp_gt_u32_e64 s[6:7], 16, v0
	v_lshlrev_b32_e32 v8, 2, v8
	s_nop 0
	v_cndmask_b32_e64 v2, v2, v1, s[6:7]
	ds_bpermute_b32 v8, v8, v2
	v_lshrrev_b32_e32 v1, 6, v4
	v_cmp_eq_u32_e64 s[6:7], 63, v0
	s_waitcnt lgkmcnt(0)
	v_add_f32_e32 v3, v2, v8
	s_and_saveexec_b64 s[30:31], s[6:7]
	v_lshl_add_u32 v6, v1, 2, s23
	ds_write_b32 v6, v3 offset:37888
	s_or_b64 exec, exec, s[30:31]
	v_cmp_gt_u32_e64 s[6:7], 32, v0
	s_waitcnt lgkmcnt(0)
	s_barrier
	v_cndmask_b32_e64 v0, v3, v2, s[6:7]
	v_cmp_eq_u32_e64 s[6:7], 1, v1
	s_and_saveexec_b64 s[30:31], s[6:7]
	s_cbranch_execz .LBB0_2195
	v_mov_b32_e32 v2, s23
	ds_read_b32 v2, v2 offset:37888
	s_waitcnt lgkmcnt(0)
	v_add_f32_e32 v0, v0, v2

.Lssdb7_done:
	s_lshl_b32 s2, s48, 6
	s_mul_i32 s4, s50, 34
	s_add_i32 s4, s4, s49
	s_ashr_i32 s5, s4, 31
	s_lshl_b64 s[4:5], s[4:5], 16
	s_lshl_b32 s6, s48, 13
	s_add_u32 s6, s34, s6
	s_addc_u32 s7, s35, 0
	v_mul_f32_e32 v59, v37, v68
	v_mul_f32_e32 v60, v36, v63
	v_mul_f32_e32 v63, v35, v67
	v_mul_f32_e32 v68, v34, v66
	ds_read2_b64 v[34:37], v61 offset0:24 offset1:26
	v_mul_f32_e32 v39, v39, v70
	v_mul_f32_e32 v38, v38, v69
	v_mul_f32_e32 v33, v33, v65
	v_mul_f32_e32 v32, v32, v64
	ds_read2_b64 v[64:67], v62 offset0:88 offset1:90
	v_cvt_pk_bf16_f32 v90, v32, v33
	v_cvt_pk_bf16_f32 v91, v68, v63
	v_cvt_pk_bf16_f32 v92, v60, v59
	v_cvt_pk_bf16_f32 v93, v38, v39
	v_mul_f32_e32 v46, v46, v77
	v_mul_f32_e32 v45, v45, v76
	s_waitcnt lgkmcnt(1)
	v_mfma_f32_32x32x16_bf16 v[16:31], v[34:37], v[90:93], v[16:31]
	ds_read2_b64 v[32:35], v61 offset0:28 offset1:30
	v_mul_f32_e32 v44, v44, v75
	v_mul_f32_e32 v43, v43, v74
	v_mul_f32_e32 v42, v42, v73
	v_mul_f32_e32 v41, v41, v72
	v_mul_f32_e32 v40, v40, v71
	v_mul_f32_e32 v47, v47, v78
	s_waitcnt lgkmcnt(1)
	v_mfma_f32_32x32x16_bf16 v[0:15], v[64:67], v[90:93], v[0:15]
	v_cvt_pk_bf16_f32 v40, v40, v41
	v_cvt_pk_bf16_f32 v41, v42, v43
	v_cvt_pk_bf16_f32 v42, v44, v45
	v_cvt_pk_bf16_f32 v43, v46, v47
	s_lshl_b32 s20, s2, 1
	v_lshlrev_b32_e32 v106, 1, v58
	s_waitcnt lgkmcnt(0)
	v_mfma_f32_32x32x16_bf16 v[16:31], v[32:35], v[40:43], v[16:31]
	v_mov_b64_e32 v[32:33], s[8:9]
	v_mad_i64_i32 v[60:61], s[4:5], v108, s44, v[32:33]
	v_lshl_add_u64 v[32:33], v[60:61], 0, s[20:21]
	v_lshl_add_u64 v[162:163], v[32:33], 0, v[106:107]
	v_add_co_u32_e32 v78, vcc, s45, v162
	v_lshl_add_u64 v[52:53], v[52:53], 0, s[20:21]
	s_nop 0
	v_addc_co_u32_e32 v79, vcc, 0, v163, vcc
	v_lshl_add_u64 v[52:53], v[52:53], 0, v[106:107]
	s_lshl_b32 s6, s48, 2
	ds_read2_b64 v[36:39], v62 offset0:92 offset1:94
	s_waitcnt lgkmcnt(0)
	v_mfma_f32_32x32x16_bf16 v[0:15], v[36:39], v[40:43], v[0:15]
	v_mul_f32_e32 v54, 0x3fb8aa3b, v54
	v_mul_f32_e32 v55, 0x3fb8aa3b, v55
	v_exp_f32_e32 v112, v54
	v_ashrrev_i32_e32 v109, 31, v108
	s_waitcnt vmcnt(0)
	v_and_b32_e32 v167, 0xffff0000, v168
	v_mfma_f32_32x32x16_bf16 v[62:77], v[240:243], v[48:51], 0
	v_mfma_f32_32x32x16_bf16 v[32:47], v[84:87], v[48:51], 0
	v_mfma_f32_32x32x16_bf16 v[78:93], v[244:247], v[48:51], 0
	v_mfma_f32_32x32x16_bf16 v[62:77], v[114:117], v[102:105], v[62:77]
	v_exp_f32_e32 v114, v55
	v_mad_i64_i32 v[54:55], s[4:5], v108, s46, v[60:61]
	v_lshl_add_u64 v[172:173], v[54:55], 0, s[20:21]
	v_lshl_add_u64 v[54:55], v[162:163], 0, s[26:27]
	v_lshlrev_b32_e32 v115, 16, v168
	v_mfma_f32_32x32x16_bf16 v[32:47], v[118:121], v[102:105], v[32:47]
	v_mfma_f32_32x32x16_bf16 v[78:93], v[122:125], v[102:105], v[78:93]
	v_mfma_f32_32x32x16_bf16 v[62:77], v[130:133], v[98:101], v[62:77]
	v_mfma_f32_32x32x16_bf16 v[32:47], v[126:129], v[98:101], v[32:47]
	v_mfma_f32_32x32x16_bf16 v[78:93], v[134:137], v[98:101], v[78:93]
	global_load_dwordx2 v[162:163], v[52:53], off offset:16
	global_load_dwordx2 v[136:137], v[52:53], off offset:32
	global_load_dwordx2 v[132:133], v[52:53], off offset:48
	global_load_dwordx2 v[128:129], v[52:53], off offset:64
	global_load_dwordx2 v[124:125], v[52:53], off offset:80
	global_load_dwordx2 v[120:121], v[52:53], off offset:96
	global_load_dwordx2 v[116:117], v[52:53], off offset:112
	v_mul_f32_e32 v52, 0xbfb8aa3b, v115
	v_mul_f32_e32 v53, 0xbfb8aa3b, v167
	v_exp_f32_e32 v52, v52
	v_exp_f32_e32 v53, v53
	v_mfma_f32_32x32x16_bf16 v[62:77], v[138:141], v[94:97], v[62:77]
	global_load_dwordx2 v[140:141], v[54:55], off offset:16
	global_load_dwordx2 v[138:139], v[54:55], off offset:32
	global_load_dwordx2 v[134:135], v[54:55], off offset:48
	global_load_dwordx2 v[130:131], v[54:55], off offset:64
	global_load_dwordx2 v[126:127], v[54:55], off offset:80
	global_load_dwordx2 v[122:123], v[54:55], off offset:96
	global_load_dwordx2 v[118:119], v[54:55], off offset:112
	s_waitcnt vmcnt(14)
	v_lshlrev_b32_e32 v54, 16, v234
	v_and_b32_e32 v55, 0xffff0000, v234
	s_nop 1
	v_pk_fma_f32 v[16:17], v[112:113], v[62:63], v[16:17] op_sel_hi:[0,1,1]
	s_waitcnt vmcnt(20)
	v_mfma_f32_32x32x16_bf16 v[78:93], v[248:251], v[94:97], v[78:93]
	v_fma_f32 v18, v112, v64, v18
	v_fma_f32 v19, v112, v65, v19
	s_waitcnt vmcnt(19)
	v_mfma_f32_32x32x16_bf16 v[32:47], v[142:145], v[94:97], v[32:47]
	s_nop 7
	v_fma_f32 v16, v114, v78, v16
	v_fma_f32 v17, v114, v79, v17
	v_add_f32_e64 v78, v52, 1.0
	v_add_f32_e64 v79, v53, 1.0
	s_waitcnt vmcnt(17)
	v_pk_fma_f32 v[16:17], v[110:111], v[54:55], v[16:17] op_sel_hi:[0,1,1]
	v_div_scale_f32 v142, s[4:5], v79, v79, v167
	v_rcp_f32_e32 v143, v142
	v_pk_fma_f32 v[18:19], v[114:115], v[80:81], v[18:19] op_sel_hi:[0,1,1]
	v_mfma_f32_32x32x16_bf16 v[48:63], v[146:149], v[48:51], 0
	v_fma_f32 v0, v112, v32, v0
	v_fma_f32 v1, v112, v33, v1
	v_fma_f32 v144, -v142, v143, 1.0
	v_fmac_f32_e32 v143, v144, v143
	v_div_scale_f32 v144, vcc, v167, v79, v167
	v_mul_f32_e32 v145, v144, v143
	v_fma_f32 v146, -v142, v145, v144
	s_waitcnt vmcnt(16)
	v_mfma_f32_32x32x16_bf16 v[48:63], v[150:153], v[102:105], v[48:63]
	v_div_scale_f32 v103, s[4:5], v78, v78, v115
	v_rcp_f32_e32 v104, v103
	v_fmac_f32_e32 v145, v146, v143
	v_fma_f32 v102, -v142, v145, v144
	v_div_fmas_f32 v102, v102, v143, v145
	v_div_fixup_f32 v79, v102, v79, v167
	s_waitcnt vmcnt(15)
	v_mfma_f32_32x32x16_bf16 v[48:63], v[154:157], v[98:101], v[48:63]
	v_fma_f32 v98, -v103, v104, 1.0
	v_fmac_f32_e32 v104, v98, v104
	v_div_scale_f32 v98, vcc, v115, v78, v115
	v_mul_f32_e32 v99, v98, v104
	v_fma_f32 v100, -v103, v99, v98
	v_fmac_f32_e32 v99, v100, v104
	s_waitcnt vmcnt(14)
	v_mfma_f32_32x32x16_bf16 v[48:63], v[158:161], v[94:97], v[48:63]
	v_fma_f32 v94, -v103, v99, v98
	v_div_fmas_f32 v94, v94, v104, v99
	v_lshlrev_b32_e32 v96, 16, v169
	v_and_b32_e32 v97, 0xffff0000, v169
	v_div_fixup_f32 v78, v94, v78, v115
	v_mul_f32_e32 v94, 0xbfb8aa3b, v96
	v_mul_f32_e32 v95, 0xbfb8aa3b, v97
	v_exp_f32_e32 v94, v94
	v_exp_f32_e32 v95, v95
	v_pk_mul_f32 v[16:17], v[16:17], v[78:79]
	v_lshlrev_b32_e32 v78, 16, v235
	v_and_b32_e32 v79, 0xffff0000, v235
	v_pk_add_f32 v[64:65], v[94:95], 1.0 op_sel_hi:[1,0]
	v_pk_fma_f32 v[18:19], v[110:111], v[78:79], v[18:19] op_sel_hi:[0,1,1]
	v_div_scale_f32 v80, s[4:5], v65, v65, v97
	v_rcp_f32_e32 v81, v80
	v_pk_fma_f32 v[0:1], v[114:115], v[48:49], v[0:1] op_sel_hi:[0,1,1]
	v_pk_fma_f32 v[2:3], v[112:113], v[34:35], v[2:3] op_sel_hi:[0,1,1]
	v_pk_fma_f32 v[2:3], v[114:115], v[50:51], v[2:3] op_sel_hi:[0,1,1]
	v_fma_f32 v78, -v80, v81, 1.0
	v_fmac_f32_e32 v81, v78, v81
	v_div_scale_f32 v78, vcc, v97, v65, v97
	v_mul_f32_e32 v79, v78, v81
	v_fma_f32 v94, -v80, v79, v78
	v_fmac_f32_e32 v79, v94, v81
	v_fma_f32 v78, -v80, v79, v78
	v_div_scale_f32 v80, s[4:5], v64, v64, v96
	v_rcp_f32_e32 v94, v80
	v_div_fmas_f32 v78, v78, v81, v79
	v_div_fixup_f32 v65, v78, v65, v97
	v_fma_f32 v78, -v80, v94, 1.0
	v_fmac_f32_e32 v94, v78, v94
	v_div_scale_f32 v78, vcc, v96, v64, v96
	v_mul_f32_e32 v79, v78, v94
	v_fma_f32 v81, -v80, v79, v78
	v_fmac_f32_e32 v79, v81, v94
	v_fma_f32 v78, -v80, v79, v78
	v_div_fmas_f32 v78, v78, v94, v79
	v_div_fixup_f32 v64, v78, v64, v96
	v_pk_mul_f32 v[18:19], v[18:19], v[64:65]
	v_cvt_pk_bf16_f32 v64, v16, v17
	v_and_b32_e32 v17, 0xffff0000, v64
	v_cvt_pk_bf16_f32 v65, v18, v19
	v_lshlrev_b32_e32 v16, 16, v64
	v_mul_f32_e32 v80, v17, v17
	s_waitcnt vmcnt(6)
	v_lshlrev_b32_e32 v81, 16, v140
	v_and_b32_e32 v94, 0xffff0000, v140
	v_lshlrev_b32_e32 v18, 16, v65
	v_fmac_f32_e32 v80, v16, v16
	v_mul_f32_e32 v78, 0xbfb8aa3b, v81
	v_mul_f32_e32 v79, 0xbfb8aa3b, v94
	v_and_b32_e32 v19, 0xffff0000, v65
	v_fmac_f32_e32 v80, v18, v18
	v_exp_f32_e32 v78, v78
	v_exp_f32_e32 v79, v79
	v_fmac_f32_e32 v80, v19, v19
	v_lshl_add_u64 v[18:19], v[172:173], 0, v[106:107]
	v_lshl_add_u64 v[16:17], v[18:19], 0, s[28:29]
	v_add_co_u32_e32 v18, vcc, s47, v18
	s_nop 1
	v_addc_co_u32_e32 v19, vcc, 0, v19, vcc
	global_store_dwordx2 v[18:19], v[64:65], off offset:1024
	v_pk_fma_f32 v[18:19], v[112:113], v[66:67], v[20:21] op_sel_hi:[0,1,1]
	v_pk_add_f32 v[20:21], v[78:79], 1.0 op_sel_hi:[1,0]
	v_pk_fma_f32 v[18:19], v[114:115], v[82:83], v[18:19] op_sel_hi:[0,1,1]
	v_div_scale_f32 v66, s[4:5], v21, v21, v94
	v_rcp_f32_e32 v67, v66
	v_lshlrev_b32_e32 v64, 16, v162
	v_and_b32_e32 v65, 0xffff0000, v162
	v_pk_fma_f32 v[18:19], v[110:111], v[64:65], v[18:19] op_sel_hi:[0,1,1]
	v_fma_f32 v64, -v66, v67, 1.0
	v_fmac_f32_e32 v67, v64, v67
	v_div_scale_f32 v64, vcc, v94, v21, v94
	v_mul_f32_e32 v65, v64, v67
	v_fma_f32 v78, -v66, v65, v64
	v_fmac_f32_e32 v65, v78, v67
	v_fma_f32 v64, -v66, v65, v64
	v_div_scale_f32 v66, s[4:5], v20, v20, v81
	v_rcp_f32_e32 v78, v66
	v_div_fmas_f32 v64, v64, v67, v65
	v_div_fixup_f32 v21, v64, v21, v94
	v_fma_f32 v64, -v66, v78, 1.0
	v_fmac_f32_e32 v78, v64, v78
	v_div_scale_f32 v64, vcc, v81, v20, v81
	v_mul_f32_e32 v65, v64, v78
	v_fma_f32 v67, -v66, v65, v64
	v_fmac_f32_e32 v65, v67, v78
	v_fma_f32 v64, -v66, v65, v64
	v_div_fmas_f32 v64, v64, v78, v65
	v_lshlrev_b32_e32 v66, 16, v141
	v_and_b32_e32 v67, 0xffff0000, v141
	v_div_fixup_f32 v20, v64, v20, v81
	v_mul_f32_e32 v64, 0xbfb8aa3b, v66
	v_mul_f32_e32 v65, 0xbfb8aa3b, v67
	v_exp_f32_e32 v64, v64
	v_exp_f32_e32 v65, v65
	v_pk_mul_f32 v[18:19], v[18:19], v[20:21]
	v_pk_fma_f32 v[20:21], v[112:113], v[68:69], v[22:23] op_sel_hi:[0,1,1]
	v_pk_fma_f32 v[20:21], v[114:115], v[84:85], v[20:21] op_sel_hi:[0,1,1]
	v_pk_add_f32 v[22:23], v[64:65], 1.0 op_sel_hi:[1,0]
	v_lshlrev_b32_e32 v64, 16, v163
	v_div_scale_f32 v68, s[4:5], v23, v23, v67
	v_rcp_f32_e32 v69, v68
	v_and_b32_e32 v65, 0xffff0000, v163
	v_pk_fma_f32 v[20:21], v[110:111], v[64:65], v[20:21] op_sel_hi:[0,1,1]
	v_cvt_pk_bf16_f32 v18, v18, v19
	v_fma_f32 v64, -v68, v69, 1.0
	v_fmac_f32_e32 v69, v64, v69
	v_div_scale_f32 v64, vcc, v67, v23, v67
	v_mul_f32_e32 v65, v64, v69
	v_fma_f32 v78, -v68, v65, v64
	v_fmac_f32_e32 v65, v78, v69
	v_fma_f32 v64, -v68, v65, v64
	v_div_scale_f32 v68, s[4:5], v22, v22, v66
	v_rcp_f32_e32 v78, v68
	v_div_fmas_f32 v64, v64, v69, v65
	v_div_fixup_f32 v23, v64, v23, v67
	v_fma_f32 v64, -v68, v78, 1.0
	v_fmac_f32_e32 v78, v64, v78
	v_div_scale_f32 v64, vcc, v66, v22, v66
	v_mul_f32_e32 v65, v64, v78
	v_fma_f32 v67, -v68, v65, v64
	v_fmac_f32_e32 v65, v67, v78
	v_fma_f32 v64, -v68, v65, v64
	v_div_fmas_f32 v64, v64, v78, v65
	v_div_fixup_f32 v22, v64, v22, v66
	v_pk_mul_f32 v[20:21], v[20:21], v[22:23]
	s_waitcnt vmcnt(6)
	v_lshlrev_b32_e32 v65, 16, v138
	v_cvt_pk_bf16_f32 v19, v20, v21
	v_and_b32_e32 v21, 0xffff0000, v18
	v_lshlrev_b32_e32 v20, 16, v18
	v_mul_f32_e32 v21, v21, v21
	v_lshlrev_b32_e32 v22, 16, v19
	v_fmac_f32_e32 v21, v20, v20
	v_and_b32_e32 v23, 0xffff0000, v19
	v_fmac_f32_e32 v21, v22, v22
	v_fmac_f32_e32 v21, v23, v23
	v_and_b32_e32 v66, 0xffff0000, v138
	v_add_f32_e32 v64, v80, v21
	v_mul_f32_e32 v20, 0xbfb8aa3b, v65
	v_mul_f32_e32 v21, 0xbfb8aa3b, v66
	v_exp_f32_e32 v20, v20
	v_exp_f32_e32 v21, v21
	global_store_dwordx2 v[16:17], v[18:19], off offset:16
	v_pk_fma_f32 v[18:19], v[112:113], v[70:71], v[24:25] op_sel_hi:[0,1,1]
	v_pk_fma_f32 v[18:19], v[114:115], v[86:87], v[18:19] op_sel_hi:[0,1,1]
	v_pk_add_f32 v[20:21], v[20:21], 1.0 op_sel_hi:[1,0]
	v_lshlrev_b32_e32 v22, 16, v136
	v_div_scale_f32 v24, s[4:5], v21, v21, v66
	v_rcp_f32_e32 v25, v24
	v_and_b32_e32 v23, 0xffff0000, v136
	v_pk_fma_f32 v[18:19], v[110:111], v[22:23], v[18:19] op_sel_hi:[0,1,1]
	v_fma_f32 v22, -v24, v25, 1.0
	v_fmac_f32_e32 v25, v22, v25
	v_div_scale_f32 v22, vcc, v66, v21, v66
	v_mul_f32_e32 v23, v22, v25
	v_fma_f32 v67, -v24, v23, v22
	v_fmac_f32_e32 v23, v67, v25
	v_fma_f32 v22, -v24, v23, v22
	v_div_scale_f32 v24, s[4:5], v20, v20, v65
	v_rcp_f32_e32 v67, v24
	v_div_fmas_f32 v22, v22, v25, v23
	v_div_fixup_f32 v21, v22, v21, v66
	v_and_b32_e32 v66, 0xffff0000, v139
	v_fma_f32 v22, -v24, v67, 1.0
	v_fmac_f32_e32 v67, v22, v67
	v_div_scale_f32 v22, vcc, v65, v20, v65
	v_mul_f32_e32 v23, v22, v67
	v_fma_f32 v25, -v24, v23, v22
	v_fmac_f32_e32 v23, v25, v67
	v_fma_f32 v22, -v24, v23, v22
	v_div_fmas_f32 v22, v22, v67, v23
	v_div_fixup_f32 v20, v22, v20, v65
	v_lshlrev_b32_e32 v65, 16, v139
	v_mul_f32_e32 v22, 0xbfb8aa3b, v65
	v_mul_f32_e32 v23, 0xbfb8aa3b, v66
	v_exp_f32_e32 v22, v22
	v_exp_f32_e32 v23, v23
	v_pk_mul_f32 v[18:19], v[18:19], v[20:21]
	v_pk_fma_f32 v[20:21], v[112:113], v[72:73], v[26:27] op_sel_hi:[0,1,1]
	v_pk_fma_f32 v[20:21], v[114:115], v[88:89], v[20:21] op_sel_hi:[0,1,1]
	v_pk_add_f32 v[22:23], v[22:23], 1.0 op_sel_hi:[1,0]
	v_lshlrev_b32_e32 v24, 16, v137
	v_div_scale_f32 v26, s[4:5], v23, v23, v66
	v_rcp_f32_e32 v27, v26
	v_and_b32_e32 v25, 0xffff0000, v137
	v_pk_fma_f32 v[20:21], v[110:111], v[24:25], v[20:21] op_sel_hi:[0,1,1]
	v_cvt_pk_bf16_f32 v18, v18, v19
	v_fma_f32 v24, -v26, v27, 1.0
	v_fmac_f32_e32 v27, v24, v27
	v_div_scale_f32 v24, vcc, v66, v23, v66
	v_mul_f32_e32 v25, v24, v27
	v_fma_f32 v67, -v26, v25, v24
	v_fmac_f32_e32 v25, v67, v27
	v_fma_f32 v24, -v26, v25, v24
	v_div_scale_f32 v26, s[4:5], v22, v22, v65
	v_rcp_f32_e32 v67, v26
	v_div_fmas_f32 v24, v24, v27, v25
	v_div_fixup_f32 v23, v24, v23, v66
	v_fma_f32 v24, -v26, v67, 1.0
	v_fmac_f32_e32 v67, v24, v67
	v_div_scale_f32 v24, vcc, v65, v22, v65
	v_mul_f32_e32 v25, v24, v67
	v_fma_f32 v27, -v26, v25, v24
	v_fmac_f32_e32 v25, v27, v67
	v_fma_f32 v24, -v26, v25, v24
	v_div_fmas_f32 v24, v24, v67, v25
	v_div_fixup_f32 v22, v24, v22, v65
	v_pk_mul_f32 v[20:21], v[20:21], v[22:23]
	s_waitcnt vmcnt(6)
	v_lshlrev_b32_e32 v24, 16, v134
	v_cvt_pk_bf16_f32 v19, v20, v21
	v_and_b32_e32 v21, 0xffff0000, v18
	v_lshlrev_b32_e32 v20, 16, v18
	v_mul_f32_e32 v21, v21, v21
	v_lshlrev_b32_e32 v22, 16, v19
	v_fmac_f32_e32 v21, v20, v20
	v_and_b32_e32 v23, 0xffff0000, v19
	v_fmac_f32_e32 v21, v22, v22
	v_fmac_f32_e32 v21, v23, v23
	v_and_b32_e32 v25, 0xffff0000, v134
	v_add_f32_e32 v26, v64, v21
	v_mul_f32_e32 v20, 0xbfb8aa3b, v24
	v_mul_f32_e32 v21, 0xbfb8aa3b, v25
	v_exp_f32_e32 v20, v20
	v_exp_f32_e32 v21, v21
	global_store_dwordx2 v[16:17], v[18:19], off offset:32
	v_pk_fma_f32 v[18:19], v[112:113], v[74:75], v[28:29] op_sel_hi:[0,1,1]
	v_pk_fma_f32 v[18:19], v[114:115], v[90:91], v[18:19] op_sel_hi:[0,1,1]
	v_pk_add_f32 v[20:21], v[20:21], 1.0 op_sel_hi:[1,0]
	v_lshlrev_b32_e32 v22, 16, v132
	v_div_scale_f32 v27, s[4:5], v21, v21, v25
	v_rcp_f32_e32 v28, v27
	v_and_b32_e32 v23, 0xffff0000, v132
	v_pk_fma_f32 v[18:19], v[110:111], v[22:23], v[18:19] op_sel_hi:[0,1,1]
	v_fma_f32 v22, -v27, v28, 1.0
	v_fmac_f32_e32 v28, v22, v28
	v_div_scale_f32 v22, vcc, v25, v21, v25
	v_mul_f32_e32 v23, v22, v28
	v_fma_f32 v29, -v27, v23, v22
	v_fmac_f32_e32 v23, v29, v28
	v_fma_f32 v22, -v27, v23, v22
	v_div_scale_f32 v27, s[4:5], v20, v20, v24
	v_rcp_f32_e32 v29, v27
	v_div_fmas_f32 v22, v22, v28, v23
	v_div_fixup_f32 v21, v22, v21, v25
	v_and_b32_e32 v28, 0xffff0000, v135
	v_fma_f32 v22, -v27, v29, 1.0
	v_fmac_f32_e32 v29, v22, v29
	v_div_scale_f32 v22, vcc, v24, v20, v24
	v_mul_f32_e32 v23, v22, v29
	v_fma_f32 v25, -v27, v23, v22
	v_fmac_f32_e32 v23, v25, v29
	v_fma_f32 v22, -v27, v23, v22
	v_div_fmas_f32 v22, v22, v29, v23
	v_lshlrev_b32_e32 v27, 16, v135
	v_div_fixup_f32 v20, v22, v20, v24
	v_mul_f32_e32 v22, 0xbfb8aa3b, v27
	v_mul_f32_e32 v23, 0xbfb8aa3b, v28
	v_exp_f32_e32 v22, v22
	v_exp_f32_e32 v23, v23
	v_pk_mul_f32 v[18:19], v[18:19], v[20:21]
	v_pk_fma_f32 v[20:21], v[112:113], v[76:77], v[30:31] op_sel_hi:[0,1,1]
	v_pk_fma_f32 v[20:21], v[114:115], v[92:93], v[20:21] op_sel_hi:[0,1,1]
	v_pk_add_f32 v[22:23], v[22:23], 1.0 op_sel_hi:[1,0]
	v_lshlrev_b32_e32 v24, 16, v133
	v_div_scale_f32 v29, s[4:5], v23, v23, v28
	v_rcp_f32_e32 v30, v29
	v_and_b32_e32 v25, 0xffff0000, v133
	v_pk_fma_f32 v[20:21], v[110:111], v[24:25], v[20:21] op_sel_hi:[0,1,1]
	v_cvt_pk_bf16_f32 v18, v18, v19
	v_fma_f32 v24, -v29, v30, 1.0
	v_fmac_f32_e32 v30, v24, v30
	v_div_scale_f32 v24, vcc, v28, v23, v28
	v_mul_f32_e32 v25, v24, v30
	v_fma_f32 v31, -v29, v25, v24
	v_fmac_f32_e32 v25, v31, v30
	v_fma_f32 v24, -v29, v25, v24
	v_div_scale_f32 v29, s[4:5], v22, v22, v27
	v_rcp_f32_e32 v31, v29
	v_div_fmas_f32 v24, v24, v30, v25
	v_div_fixup_f32 v23, v24, v23, v28
	v_fma_f32 v24, -v29, v31, 1.0
	v_fmac_f32_e32 v31, v24, v31
	v_div_scale_f32 v24, vcc, v27, v22, v27
	v_mul_f32_e32 v25, v24, v31
	v_fma_f32 v28, -v29, v25, v24
	v_fmac_f32_e32 v25, v28, v31
	v_fma_f32 v24, -v29, v25, v24
	v_div_fmas_f32 v24, v24, v31, v25
	v_div_fixup_f32 v22, v24, v22, v27
	v_pk_mul_f32 v[20:21], v[20:21], v[22:23]
	s_waitcnt vmcnt(6)
	v_and_b32_e32 v24, 0xffff0000, v130
	v_cvt_pk_bf16_f32 v19, v20, v21
	v_and_b32_e32 v21, 0xffff0000, v18
	v_lshlrev_b32_e32 v20, 16, v18
	v_mul_f32_e32 v21, v21, v21
	v_lshlrev_b32_e32 v22, 16, v19
	v_fmac_f32_e32 v21, v20, v20
	v_and_b32_e32 v23, 0xffff0000, v19
	v_fmac_f32_e32 v21, v22, v22
	v_fmac_f32_e32 v21, v23, v23
	v_lshlrev_b32_e32 v23, 16, v130
	v_add_f32_e32 v22, v26, v21
	v_mul_f32_e32 v20, 0xbfb8aa3b, v23
	v_mul_f32_e32 v21, 0xbfb8aa3b, v24
	v_exp_f32_e32 v20, v20
	v_exp_f32_e32 v21, v21
	global_store_dwordx2 v[16:17], v[18:19], off offset:48
	v_pk_add_f32 v[18:19], v[20:21], 1.0 op_sel_hi:[1,0]
	s_nop 0
	v_div_scale_f32 v25, s[4:5], v19, v19, v24
	v_rcp_f32_e32 v26, v25
	v_lshlrev_b32_e32 v20, 16, v128
	v_and_b32_e32 v21, 0xffff0000, v128
	v_pk_fma_f32 v[0:1], v[110:111], v[20:21], v[0:1] op_sel_hi:[0,1,1]
	v_fma_f32 v20, -v25, v26, 1.0
	v_fmac_f32_e32 v26, v20, v26
	v_div_scale_f32 v20, vcc, v24, v19, v24
	v_mul_f32_e32 v21, v20, v26
	v_fma_f32 v27, -v25, v21, v20
	v_fmac_f32_e32 v21, v27, v26
	v_fma_f32 v20, -v25, v21, v20
	v_div_scale_f32 v25, s[4:5], v18, v18, v23
	v_rcp_f32_e32 v27, v25
	v_div_fmas_f32 v20, v20, v26, v21
	v_div_fixup_f32 v19, v20, v19, v24
	v_fma_f32 v20, -v25, v27, 1.0
	v_fmac_f32_e32 v27, v20, v27
	v_div_scale_f32 v20, vcc, v23, v18, v23
	v_mul_f32_e32 v21, v20, v27
	v_fma_f32 v24, -v25, v21, v20
	v_fmac_f32_e32 v21, v24, v27
	v_fma_f32 v20, -v25, v21, v20
	v_div_fmas_f32 v20, v20, v27, v21
	v_div_fixup_f32 v18, v20, v18, v23
	v_lshlrev_b32_e32 v23, 16, v131
	v_and_b32_e32 v24, 0xffff0000, v131
	v_mul_f32_e32 v20, 0xbfb8aa3b, v23
	v_mul_f32_e32 v21, 0xbfb8aa3b, v24
	v_exp_f32_e32 v20, v20
	v_exp_f32_e32 v21, v21
	v_pk_mul_f32 v[0:1], v[0:1], v[18:19]
	v_pk_add_f32 v[18:19], v[20:21], 1.0 op_sel_hi:[1,0]
	s_nop 0
	v_div_scale_f32 v25, s[4:5], v19, v19, v24
	v_rcp_f32_e32 v26, v25
	v_lshlrev_b32_e32 v20, 16, v129
	v_and_b32_e32 v21, 0xffff0000, v129
	v_pk_fma_f32 v[2:3], v[110:111], v[20:21], v[2:3] op_sel_hi:[0,1,1]
	v_fma_f32 v20, -v25, v26, 1.0
	v_fmac_f32_e32 v26, v20, v26
	v_div_scale_f32 v20, vcc, v24, v19, v24
	v_mul_f32_e32 v21, v20, v26
	v_fma_f32 v27, -v25, v21, v20
	v_fmac_f32_e32 v21, v27, v26
	v_fma_f32 v20, -v25, v21, v20
	v_div_scale_f32 v25, s[4:5], v18, v18, v23
	v_rcp_f32_e32 v27, v25
	v_div_fmas_f32 v20, v20, v26, v21
	v_div_fixup_f32 v19, v20, v19, v24
	v_cvt_pk_bf16_f32 v0, v0, v1
	v_fma_f32 v20, -v25, v27, 1.0
	v_fmac_f32_e32 v27, v20, v27
	v_div_scale_f32 v20, vcc, v23, v18, v23
	v_mul_f32_e32 v21, v20, v27
	v_fma_f32 v24, -v25, v21, v20
	v_fmac_f32_e32 v21, v24, v27
	v_fma_f32 v20, -v25, v21, v20
	v_div_fmas_f32 v20, v20, v27, v21
	v_div_fixup_f32 v18, v20, v18, v23
	v_pk_mul_f32 v[2:3], v[2:3], v[18:19]
	s_waitcnt vmcnt(6)
	v_and_b32_e32 v20, 0xffff0000, v126
	v_cvt_pk_bf16_f32 v1, v2, v3
	v_and_b32_e32 v3, 0xffff0000, v0
	v_lshlrev_b32_e32 v2, 16, v0
	v_mul_f32_e32 v3, v3, v3
	v_lshlrev_b32_e32 v18, 16, v1
	v_fmac_f32_e32 v3, v2, v2
	v_and_b32_e32 v19, 0xffff0000, v1
	v_fmac_f32_e32 v3, v18, v18
	v_fmac_f32_e32 v3, v19, v19
	v_lshlrev_b32_e32 v19, 16, v126
	v_add_f32_e32 v18, v22, v3
	v_mul_f32_e32 v2, 0xbfb8aa3b, v19
	v_mul_f32_e32 v3, 0xbfb8aa3b, v20
	v_exp_f32_e32 v2, v2
	v_exp_f32_e32 v3, v3
	global_store_dwordx2 v[16:17], v[0:1], off offset:64
	v_pk_fma_f32 v[0:1], v[112:113], v[36:37], v[4:5] op_sel_hi:[0,1,1]
	v_pk_fma_f32 v[0:1], v[114:115], v[52:53], v[0:1] op_sel_hi:[0,1,1]
	v_pk_add_f32 v[2:3], v[2:3], 1.0 op_sel_hi:[1,0]
	v_lshlrev_b32_e32 v4, 16, v124
	v_div_scale_f32 v21, s[4:5], v3, v3, v20
	v_rcp_f32_e32 v22, v21
	v_and_b32_e32 v5, 0xffff0000, v124
	v_pk_fma_f32 v[0:1], v[110:111], v[4:5], v[0:1] op_sel_hi:[0,1,1]
	v_fma_f32 v4, -v21, v22, 1.0
	v_fmac_f32_e32 v22, v4, v22
	v_div_scale_f32 v4, vcc, v20, v3, v20
	v_mul_f32_e32 v5, v4, v22
	v_fma_f32 v23, -v21, v5, v4
	v_fmac_f32_e32 v5, v23, v22
	v_fma_f32 v4, -v21, v5, v4
	v_div_scale_f32 v21, s[4:5], v2, v2, v19
	v_rcp_f32_e32 v23, v21
	v_div_fmas_f32 v4, v4, v22, v5
	v_div_fixup_f32 v3, v4, v3, v20
	v_fma_f32 v4, -v21, v23, 1.0
	v_fmac_f32_e32 v23, v4, v23
	v_div_scale_f32 v4, vcc, v19, v2, v19
	v_mul_f32_e32 v5, v4, v23
	v_fma_f32 v20, -v21, v5, v4
	v_fmac_f32_e32 v5, v20, v23
	v_fma_f32 v4, -v21, v5, v4
	v_div_fmas_f32 v4, v4, v23, v5
	v_div_fixup_f32 v2, v4, v2, v19
	v_lshlrev_b32_e32 v19, 16, v127
	v_and_b32_e32 v20, 0xffff0000, v127
	v_mul_f32_e32 v4, 0xbfb8aa3b, v19
	v_mul_f32_e32 v5, 0xbfb8aa3b, v20
	v_exp_f32_e32 v4, v4
	v_exp_f32_e32 v5, v5
	v_pk_mul_f32 v[0:1], v[0:1], v[2:3]
	v_pk_fma_f32 v[2:3], v[112:113], v[38:39], v[6:7] op_sel_hi:[0,1,1]
	v_pk_fma_f32 v[2:3], v[114:115], v[54:55], v[2:3] op_sel_hi:[0,1,1]
	v_pk_add_f32 v[4:5], v[4:5], 1.0 op_sel_hi:[1,0]
	v_lshlrev_b32_e32 v6, 16, v125
	v_div_scale_f32 v21, s[4:5], v5, v5, v20
	v_rcp_f32_e32 v22, v21
	v_and_b32_e32 v7, 0xffff0000, v125
	v_pk_fma_f32 v[2:3], v[110:111], v[6:7], v[2:3] op_sel_hi:[0,1,1]
	v_cvt_pk_bf16_f32 v0, v0, v1
	v_fma_f32 v6, -v21, v22, 1.0
	v_fmac_f32_e32 v22, v6, v22
	v_div_scale_f32 v6, vcc, v20, v5, v20
	v_mul_f32_e32 v7, v6, v22
	v_fma_f32 v23, -v21, v7, v6
	v_fmac_f32_e32 v7, v23, v22
	v_fma_f32 v6, -v21, v7, v6
	v_div_scale_f32 v21, s[4:5], v4, v4, v19
	v_rcp_f32_e32 v23, v21
	v_div_fmas_f32 v6, v6, v22, v7
	v_div_fixup_f32 v5, v6, v5, v20
	v_fma_f32 v6, -v21, v23, 1.0
	v_fmac_f32_e32 v23, v6, v23
	v_div_scale_f32 v6, vcc, v19, v4, v19
	v_mul_f32_e32 v7, v6, v23
	v_fma_f32 v20, -v21, v7, v6
	v_fmac_f32_e32 v7, v20, v23
	v_fma_f32 v6, -v21, v7, v6
	v_div_fmas_f32 v6, v6, v23, v7
	v_div_fixup_f32 v4, v6, v4, v19
	v_pk_mul_f32 v[2:3], v[2:3], v[4:5]
	s_waitcnt vmcnt(6)
	v_lshlrev_b32_e32 v19, 16, v122
	v_cvt_pk_bf16_f32 v1, v2, v3
	v_and_b32_e32 v3, 0xffff0000, v0
	v_lshlrev_b32_e32 v2, 16, v0
	v_mul_f32_e32 v6, v3, v3
	v_and_b32_e32 v20, 0xffff0000, v122
	v_fmac_f32_e32 v6, v2, v2
	v_mul_f32_e32 v2, 0xbfb8aa3b, v19
	v_mul_f32_e32 v3, 0xbfb8aa3b, v20
	v_exp_f32_e32 v2, v2
	v_exp_f32_e32 v3, v3
	v_lshlrev_b32_e32 v4, 16, v1
	v_and_b32_e32 v5, 0xffff0000, v1
	v_fmac_f32_e32 v6, v4, v4
	v_pk_add_f32 v[2:3], v[2:3], 1.0 op_sel_hi:[1,0]
	v_fmac_f32_e32 v6, v5, v5
	v_pk_fma_f32 v[4:5], v[112:113], v[40:41], v[8:9] op_sel_hi:[0,1,1]
	v_div_scale_f32 v8, s[4:5], v3, v3, v20
	v_rcp_f32_e32 v9, v8
	v_add_f32_e32 v18, v18, v6
	v_pk_fma_f32 v[4:5], v[114:115], v[56:57], v[4:5] op_sel_hi:[0,1,1]
	v_lshlrev_b32_e32 v6, 16, v120
	v_and_b32_e32 v7, 0xffff0000, v120
	v_pk_fma_f32 v[4:5], v[110:111], v[6:7], v[4:5] op_sel_hi:[0,1,1]
	v_fma_f32 v6, -v8, v9, 1.0
	v_fmac_f32_e32 v9, v6, v9
	v_div_scale_f32 v6, vcc, v20, v3, v20
	v_mul_f32_e32 v7, v6, v9
	v_fma_f32 v21, -v8, v7, v6
	v_fmac_f32_e32 v7, v21, v9
	v_fma_f32 v6, -v8, v7, v6
	v_div_scale_f32 v8, s[4:5], v2, v2, v19
	v_rcp_f32_e32 v21, v8
	v_div_fmas_f32 v6, v6, v9, v7
	v_div_fixup_f32 v3, v6, v3, v20
	v_and_b32_e32 v20, 0xffff0000, v123
	v_fma_f32 v6, -v8, v21, 1.0
	v_fmac_f32_e32 v21, v6, v21
	v_div_scale_f32 v6, vcc, v19, v2, v19
	v_mul_f32_e32 v7, v6, v21
	v_fma_f32 v9, -v8, v7, v6
	v_fmac_f32_e32 v7, v9, v21
	v_fma_f32 v6, -v8, v7, v6
	v_div_fmas_f32 v6, v6, v21, v7
	v_div_fixup_f32 v2, v6, v2, v19
	v_lshlrev_b32_e32 v19, 16, v123
	v_mul_f32_e32 v6, 0xbfb8aa3b, v19
	v_mul_f32_e32 v7, 0xbfb8aa3b, v20
	v_exp_f32_e32 v6, v6
	v_exp_f32_e32 v7, v7
	v_pk_mul_f32 v[2:3], v[4:5], v[2:3]
	v_pk_fma_f32 v[4:5], v[112:113], v[42:43], v[10:11] op_sel_hi:[0,1,1]
	v_pk_fma_f32 v[4:5], v[114:115], v[58:59], v[4:5] op_sel_hi:[0,1,1]
	v_pk_add_f32 v[6:7], v[6:7], 1.0 op_sel_hi:[1,0]
	v_lshlrev_b32_e32 v8, 16, v121
	v_div_scale_f32 v10, s[4:5], v7, v7, v20
	v_rcp_f32_e32 v11, v10
	v_and_b32_e32 v9, 0xffff0000, v121
	v_pk_fma_f32 v[4:5], v[110:111], v[8:9], v[4:5] op_sel_hi:[0,1,1]
	v_fma_f32 v8, -v10, v11, 1.0
	v_fmac_f32_e32 v11, v8, v11
	v_div_scale_f32 v8, vcc, v20, v7, v20
	v_mul_f32_e32 v9, v8, v11
	v_fma_f32 v21, -v10, v9, v8
	v_fmac_f32_e32 v9, v21, v11
	v_fma_f32 v8, -v10, v9, v8
	v_div_scale_f32 v10, s[4:5], v6, v6, v19
	v_rcp_f32_e32 v21, v10
	v_div_fmas_f32 v8, v8, v11, v9
	v_div_fixup_f32 v7, v8, v7, v20
	v_fma_f32 v8, -v10, v21, 1.0
	v_fmac_f32_e32 v21, v8, v21
	v_div_scale_f32 v8, vcc, v19, v6, v19
	v_mul_f32_e32 v9, v8, v21
	v_fma_f32 v11, -v10, v9, v8
	v_fmac_f32_e32 v9, v11, v21
	v_fma_f32 v8, -v10, v9, v8
	v_div_fmas_f32 v8, v8, v21, v9
	v_div_fixup_f32 v6, v8, v6, v19
	v_pk_mul_f32 v[4:5], v[4:5], v[6:7]
	v_cvt_pk_bf16_f32 v6, v2, v3
	v_and_b32_e32 v3, 0xffff0000, v6
	v_lshlrev_b32_e32 v2, 16, v6
	v_mul_f32_e32 v8, v3, v3
	s_waitcnt vmcnt(5)
	v_lshlrev_b32_e32 v10, 16, v118
	v_and_b32_e32 v11, 0xffff0000, v118
	v_fmac_f32_e32 v8, v2, v2
	v_mul_f32_e32 v2, 0xbfb8aa3b, v10
	v_mul_f32_e32 v3, 0xbfb8aa3b, v11
	v_exp_f32_e32 v2, v2
	v_exp_f32_e32 v3, v3
	v_cvt_pk_bf16_f32 v7, v4, v5
	v_lshlrev_b32_e32 v4, 16, v7
	v_and_b32_e32 v5, 0xffff0000, v7
	v_fmac_f32_e32 v8, v4, v4
	v_pk_add_f32 v[2:3], v[2:3], 1.0 op_sel_hi:[1,0]
	v_fmac_f32_e32 v8, v5, v5
	v_pk_fma_f32 v[4:5], v[112:113], v[44:45], v[12:13] op_sel_hi:[0,1,1]
	v_div_scale_f32 v12, s[4:5], v3, v3, v11
	v_rcp_f32_e32 v13, v12
	v_add_f32_e32 v18, v18, v8
	v_pk_fma_f32 v[4:5], v[114:115], v[60:61], v[4:5] op_sel_hi:[0,1,1]
	v_lshlrev_b32_e32 v8, 16, v116
	v_and_b32_e32 v9, 0xffff0000, v116
	v_pk_fma_f32 v[4:5], v[110:111], v[8:9], v[4:5] op_sel_hi:[0,1,1]
	v_fma_f32 v8, -v12, v13, 1.0
	v_fmac_f32_e32 v13, v8, v13
	v_div_scale_f32 v8, vcc, v11, v3, v11
	v_mul_f32_e32 v9, v8, v13
	v_fma_f32 v19, -v12, v9, v8
	v_fmac_f32_e32 v9, v19, v13
	v_fma_f32 v8, -v12, v9, v8
	v_div_scale_f32 v12, s[4:5], v2, v2, v10
	v_rcp_f32_e32 v19, v12
	v_div_fmas_f32 v8, v8, v13, v9
	v_div_fixup_f32 v3, v8, v3, v11
	v_and_b32_e32 v13, 0xffff0000, v119
	v_fma_f32 v8, -v12, v19, 1.0
	v_fmac_f32_e32 v19, v8, v19
	v_div_scale_f32 v8, vcc, v10, v2, v10
	v_mul_f32_e32 v9, v8, v19
	v_fma_f32 v11, -v12, v9, v8
	v_fmac_f32_e32 v9, v11, v19
	v_fma_f32 v8, -v12, v9, v8
	v_div_fmas_f32 v8, v8, v19, v9
	v_lshlrev_b32_e32 v12, 16, v119
	v_div_fixup_f32 v2, v8, v2, v10
	v_mul_f32_e32 v8, 0xbfb8aa3b, v12
	v_mul_f32_e32 v9, 0xbfb8aa3b, v13
	v_exp_f32_e32 v8, v8
	v_exp_f32_e32 v9, v9
	v_pk_mul_f32 v[2:3], v[4:5], v[2:3]
	v_pk_fma_f32 v[4:5], v[112:113], v[46:47], v[14:15] op_sel_hi:[0,1,1]
	v_pk_fma_f32 v[4:5], v[114:115], v[62:63], v[4:5] op_sel_hi:[0,1,1]
	v_pk_add_f32 v[8:9], v[8:9], 1.0 op_sel_hi:[1,0]
	v_lshlrev_b32_e32 v10, 16, v117
	v_div_scale_f32 v14, s[4:5], v9, v9, v13
	v_rcp_f32_e32 v15, v14
	v_and_b32_e32 v11, 0xffff0000, v117
	v_pk_fma_f32 v[4:5], v[110:111], v[10:11], v[4:5] op_sel_hi:[0,1,1]
	v_fma_f32 v10, -v14, v15, 1.0
	v_fmac_f32_e32 v15, v10, v15
	v_div_scale_f32 v10, vcc, v13, v9, v13
	v_mul_f32_e32 v11, v10, v15
	v_fma_f32 v19, -v14, v11, v10
	v_fmac_f32_e32 v11, v19, v15
	v_fma_f32 v10, -v14, v11, v10
	v_div_scale_f32 v14, s[4:5], v8, v8, v12
	v_rcp_f32_e32 v19, v14
	v_div_fmas_f32 v10, v10, v15, v11
	v_div_fixup_f32 v9, v10, v9, v13
	v_fma_f32 v10, -v14, v19, 1.0
	v_fmac_f32_e32 v19, v10, v19
	v_div_scale_f32 v10, vcc, v12, v8, v12
	v_mul_f32_e32 v11, v10, v19
	v_fma_f32 v13, -v14, v11, v10
	v_fmac_f32_e32 v11, v13, v19
	v_fma_f32 v10, -v14, v11, v10
	v_div_fmas_f32 v10, v10, v19, v11
	v_div_fixup_f32 v8, v10, v8, v12
	v_pk_mul_f32 v[4:5], v[4:5], v[8:9]
	v_cvt_pk_bf16_f32 v8, v2, v3
	v_and_b32_e32 v3, 0xffff0000, v8
	v_cvt_pk_bf16_f32 v9, v4, v5
	v_lshlrev_b32_e32 v2, 16, v8
	v_mul_f32_e32 v3, v3, v3
	v_lshlrev_b32_e32 v4, 16, v9
	v_fmac_f32_e32 v3, v2, v2
	v_and_b32_e32 v5, 0xffff0000, v9
	v_fmac_f32_e32 v3, v4, v4
	v_fmac_f32_e32 v3, v5, v5
	v_add_f32_e32 v2, v18, v3
	v_xor_b32_e32 v3, 32, v165
	v_add_u32_e32 v4, 64, v113
	v_cmp_lt_i32_e32 vcc, v3, v4
	global_store_dwordx2 v[16:17], v[0:1], off offset:80
	global_store_dwordx2 v[16:17], v[6:7], off offset:96
	global_store_dwordx2 v[16:17], v[8:9], off offset:112
	v_cndmask_b32_e32 v3, v165, v3, vcc
	v_lshlrev_b32_e32 v3, 2, v3
	ds_bpermute_b32 v3, v3, v2
	v_cmp_eq_u32_e32 vcc, 0, v111
	s_and_saveexec_b64 s[30:31], vcc
	s_cbranch_execz .LBB0_2184
	v_lshlrev_b64 v[0:1], 5, v[108:109]
	v_lshl_add_u64 v[0:1], s[18:19], 0, v[0:1]
	s_mov_b32 s7, s21
	v_lshl_add_u64 v[0:1], v[0:1], 0, s[6:7]
	s_waitcnt lgkmcnt(0)
	v_add_f32_e32 v2, v2, v3
	global_store_dword v[0:1], v2, off
	s_branch .LBB0_2184
